# C3: ctx Fourier j-loop shares the 64x128 proj tile through LDS (each wave LDS-DMAs 2 of 16 fragments one iteration ahead, double-buffered, one block barrier per j) instead of all 8 waves loading all 1
# baseline (speedup 1.0000x reference)
.LBB0_306:
	s_andn2_b64 vcc, exec, s[2:3]
	s_cbranch_vccnz .LBB0_310
	v_lshrrev_b32_e32 v0, 1, v235
	v_readlane_b32 s0, v251, 54
	v_bfe_u32 v130, v206, 6, 2
	v_and_b32_e32 v128, 16, v0
	v_readlane_b32 s1, v251, 55
	v_lshlrev_b32_e32 v0, 4, v248
	v_mov_b32_e32 v16, 0
	v_lshl_add_u64 v[100:101], s[0:1], 0, v[128:129]
	v_lshl_or_b32 v128, v130, 14, v0
	v_lshl_add_u64 v[102:103], s[12:13], 0, v[128:129]
	s_mov_b64 s[0:1], 0x2400
	v_lshl_add_u64 v[106:107], v[102:103], 0, s[0:1]
	s_mov_b64 s[0:1], 0x2800
	v_lshl_add_u64 v[108:109], v[102:103], 0, s[0:1]
	s_mov_b64 s[0:1], 0x2c00
	v_lshl_add_u64 v[110:111], v[102:103], 0, s[0:1]
	s_mov_b64 s[0:1], 0x1000
	v_lshl_add_u64 v[112:113], v[102:103], 0, s[0:1]
	s_mov_b64 s[0:1], 0x3000
	v_lshl_add_u64 v[114:115], v[102:103], 0, s[0:1]
	s_mov_b64 s[0:1], 0x1400
	v_lshl_add_u64 v[116:117], v[102:103], 0, s[0:1]
	s_mov_b64 s[0:1], 0x3400
	v_lshl_add_u64 v[118:119], v[102:103], 0, s[0:1]
	s_mov_b64 s[0:1], 0x3800
	v_lshl_add_u64 v[122:123], v[102:103], 0, s[0:1]
	s_mov_b64 s[0:1], 0x1c00
	v_lshl_add_u64 v[124:125], v[102:103], 0, s[0:1]
	s_mov_b64 s[0:1], 0x3c00
	v_lshl_add_u64 v[126:127], v[102:103], 0, s[0:1]
	v_lshlrev_b32_e32 v0, 12, v166
	v_readlane_b32 s0, v254, 23
	v_lshl_add_u64 v[104:105], v[102:103], 0, s[20:21]
	v_lshl_add_u64 v[120:121], v[102:103], 0, s[30:31]
	v_add3_u32 v128, s0, v0, v248
	v_readlane_b32 s0, v251, 52
	v_mov_b32_e32 v17, v16
	v_mov_b32_e32 v18, v16
	v_add_u32_e32 v131, s0, v164
	s_mov_b32 s0, 0
	v_mov_b32_e32 v19, v16
	v_mov_b32_e32 v20, v16
	v_mov_b32_e32 v21, v16
	v_mov_b32_e32 v22, v16
	v_mov_b32_e32 v23, v16
	v_mov_b32_e32 v24, v16
	v_mov_b32_e32 v25, v16
	v_mov_b32_e32 v26, v16
	v_mov_b32_e32 v27, v16
	v_mov_b32_e32 v28, v16
	v_mov_b32_e32 v29, v16
	v_mov_b32_e32 v30, v16
	v_mov_b32_e32 v31, v16
	v_mov_b32_e32 v0, v16
	v_mov_b32_e32 v1, v16
	v_mov_b32_e32 v2, v16
	v_mov_b32_e32 v3, v16
	v_mov_b32_e32 v4, v16
	v_mov_b32_e32 v5, v16
	v_mov_b32_e32 v6, v16
	v_mov_b32_e32 v7, v16
	v_mov_b32_e32 v8, v16
	v_mov_b32_e32 v9, v16
	v_mov_b32_e32 v10, v16
	v_mov_b32_e32 v11, v16
	v_mov_b32_e32 v12, v16
	v_mov_b32_e32 v13, v16
	v_mov_b32_e32 v14, v16
	v_mov_b32_e32 v15, v16
	s_movk_i32 s1, 0x3800
	v_mbcnt_lo_u32_b32 v236, -1, 0
	v_mbcnt_hi_u32_b32 v236, -1, v236
	v_lshlrev_b32_e32 v236, 4, v236
	s_lshr_b32 s8, s87, 6
	s_lshr_b32 s9, s8, 2
	s_and_b32 s10, s8, 3
	s_lshl_b32 s6, s10, 6
	s_mov_b32 s7, 0
	s_lshl_b32 s9, s9, 5
	s_lshl_b32 s8, s87, 5
	v_add_u32_e32 v237, s9, v131
	v_mad_i64_i32 v[200:201], s[2:3], v237, s1, v[100:101]
	s_nop 1
	v_lshl_add_u64 v[200:201], v[200:201], 0, s[6:7]
	v_lshl_add_u64 v[202:203], v[200:201], 0, 32
	s_mov_b32 m0, s8
	s_nop 0
	global_load_lds_dwordx4 v[200:201], off
	s_add_i32 m0, s8, 0x400
	s_nop 0
	global_load_lds_dwordx4 v[202:203], off
	s_add_i32 s9, s9, 64
	s_mov_b32 s10, 0
.LBB0_308:
	v_add_u32_e32 v32, 32, v131
	s_waitcnt vmcnt(0)
	s_barrier
	s_xor_b32 s11, s10, 0x4000
	v_add_u32_e32 v237, s9, v131
	v_mad_i64_i32 v[200:201], s[2:3], v237, s1, v[100:101]
	v_add_u32_e32 v204, s10, v236
	v_lshl_add_u64 v[200:201], v[200:201], 0, s[6:7]
	s_add_i32 s5, s8, s11
	v_lshl_add_u64 v[202:203], v[200:201], 0, 32
	s_mov_b32 m0, s5
	s_nop 0
	global_load_lds_dwordx4 v[200:201], off
	s_add_i32 m0, s5, 0x400
	s_nop 0
	global_load_lds_dwordx4 v[202:203], off
	s_mov_b32 s10, s11
	global_load_dwordx4 v[32:35], v[102:103], off
	global_load_dwordx4 v[96:99], v[102:103], off offset:1024
	global_load_dwordx4 v[36:39], v[104:105], off
	global_load_dwordx4 v[132:135], v[106:107], off
	ds_read_b128 v[40:43], v204
	ds_read_b128 v[136:139], v204 offset:1024
	ds_read_b128 v[44:47], v204 offset:8192
	ds_read_b128 v[140:143], v204 offset:9216
	global_load_dwordx4 v[168:171], v[102:103], off offset:2048
	global_load_dwordx4 v[172:175], v[102:103], off offset:3072
	global_load_dwordx4 v[176:179], v[108:109], off
	global_load_dwordx4 v[180:183], v[110:111], off
	ds_read_b128 v[184:187], v204 offset:2048
	ds_read_b128 v[188:191], v204 offset:3072
	ds_read_b128 v[192:195], v204 offset:10240
	ds_read_b128 v[196:199], v204 offset:11264
	s_waitcnt vmcnt(4) lgkmcnt(4)
	v_mfma_f32_32x32x16_bf16 v[80:95], v[40:43], v[32:35], 0
	v_mfma_f32_32x32x16_bf16 v[64:79], v[40:43], v[36:39], 0
	v_mfma_f32_32x32x16_bf16 v[48:63], v[44:47], v[32:35], 0
	v_mfma_f32_32x32x16_bf16 v[32:47], v[44:47], v[36:39], 0
	v_mfma_f32_32x32x16_bf16 v[80:95], v[136:139], v[96:99], v[80:95]
	v_mfma_f32_32x32x16_bf16 v[64:79], v[136:139], v[132:135], v[64:79]
	v_mfma_f32_32x32x16_bf16 v[48:63], v[140:143], v[96:99], v[48:63]
	v_mfma_f32_32x32x16_bf16 v[32:47], v[140:143], v[132:135], v[32:47]
	global_load_dwordx4 v[96:99], v[112:113], off
	global_load_dwordx4 v[132:135], v[114:115], off
	global_load_dwordx4 v[136:139], v[116:117], off
	global_load_dwordx4 v[140:143], v[118:119], off
	ds_read_b128 v[144:147], v204 offset:4096
	ds_read_b128 v[148:151], v204 offset:5120
	ds_read_b128 v[152:155], v204 offset:12288
	ds_read_b128 v[156:159], v204 offset:13312
	s_waitcnt vmcnt(4) lgkmcnt(4)
	v_mfma_f32_32x32x16_bf16 v[80:95], v[184:187], v[168:171], v[80:95]
	v_mfma_f32_32x32x16_bf16 v[64:79], v[184:187], v[176:179], v[64:79]
	v_mfma_f32_32x32x16_bf16 v[48:63], v[192:195], v[168:171], v[48:63]
	v_mfma_f32_32x32x16_bf16 v[32:47], v[192:195], v[176:179], v[32:47]
	v_mfma_f32_32x32x16_bf16 v[80:95], v[188:191], v[172:175], v[80:95]
	v_mfma_f32_32x32x16_bf16 v[64:79], v[188:191], v[180:183], v[64:79]
	v_mfma_f32_32x32x16_bf16 v[48:63], v[196:199], v[172:175], v[48:63]
	v_mfma_f32_32x32x16_bf16 v[32:47], v[196:199], v[180:183], v[32:47]
	global_load_dwordx4 v[168:171], v[120:121], off
	global_load_dwordx4 v[172:175], v[122:123], off
	global_load_dwordx4 v[176:179], v[124:125], off
	global_load_dwordx4 v[180:183], v[126:127], off
	ds_read_b128 v[184:187], v204 offset:6144
	ds_read_b128 v[188:191], v204 offset:7168
	ds_read_b128 v[192:195], v204 offset:14336
	ds_read_b128 v[196:199], v204 offset:15360
	s_waitcnt vmcnt(4) lgkmcnt(4)
	v_mfma_f32_32x32x16_bf16 v[80:95], v[144:147], v[96:99], v[80:95]
	v_mfma_f32_32x32x16_bf16 v[64:79], v[144:147], v[132:135], v[64:79]
	v_mfma_f32_32x32x16_bf16 v[48:63], v[152:155], v[96:99], v[48:63]
	v_mfma_f32_32x32x16_bf16 v[32:47], v[152:155], v[132:135], v[32:47]
	v_mfma_f32_32x32x16_bf16 v[80:95], v[148:151], v[136:139], v[80:95]
	v_mfma_f32_32x32x16_bf16 v[64:79], v[148:151], v[140:143], v[64:79]
	v_mfma_f32_32x32x16_bf16 v[48:63], v[156:159], v[136:139], v[48:63]
	v_mfma_f32_32x32x16_bf16 v[32:47], v[156:159], v[140:143], v[32:47]
	s_waitcnt vmcnt(0) lgkmcnt(0)
	v_mfma_f32_32x32x16_bf16 v[80:95], v[184:187], v[168:171], v[80:95]
	v_mfma_f32_32x32x16_bf16 v[64:79], v[184:187], v[172:175], v[64:79]
	v_mfma_f32_32x32x16_bf16 v[48:63], v[192:195], v[168:171], v[48:63]
	v_mfma_f32_32x32x16_bf16 v[32:47], v[192:195], v[172:175], v[32:47]
	v_mfma_f32_32x32x16_bf16 v[80:95], v[188:191], v[176:179], v[80:95]
	v_mfma_f32_32x32x16_bf16 v[64:79], v[188:191], v[180:183], v[64:79]
	v_mfma_f32_32x32x16_bf16 v[48:63], v[196:199], v[176:179], v[48:63]
	v_mfma_f32_32x32x16_bf16 v[32:47], v[196:199], v[180:183], v[32:47]
	s_nop 8
	v_cvt_pk_bf16_f32 v97, v82, v83
	v_cvt_pk_bf16_f32 v82, v92, v93
	v_add_u32_e32 v92, s0, v128
	v_cvt_pk_bf16_f32 v96, v80, v81
	v_cvt_pk_bf16_f32 v98, v84, v85
	v_cvt_pk_bf16_f32 v99, v86, v87
	v_cvt_pk_bf16_f32 v80, v88, v89
	v_cvt_pk_bf16_f32 v84, v64, v65
	v_cvt_pk_bf16_f32 v85, v66, v67
	v_cvt_pk_bf16_f32 v86, v68, v69
	v_cvt_pk_bf16_f32 v87, v70, v71
	v_cvt_pk_bf16_f32 v64, v72, v73
	v_cvt_pk_bf16_f32 v66, v76, v77
	v_cvt_pk_bf16_f32 v68, v48, v49
	v_cvt_pk_bf16_f32 v69, v50, v51
	v_cvt_pk_bf16_f32 v70, v52, v53
	v_cvt_pk_bf16_f32 v71, v54, v55
	v_cvt_pk_bf16_f32 v48, v56, v57
	v_cvt_pk_bf16_f32 v50, v60, v61
	v_cvt_pk_bf16_f32 v52, v32, v33
	v_cvt_pk_bf16_f32 v53, v34, v35
	v_cvt_pk_bf16_f32 v54, v36, v37
	v_cvt_pk_bf16_f32 v32, v40, v41
	v_cvt_pk_bf16_f32 v34, v44, v45
	v_add_u32_e32 v36, 0x1800, v92
	v_add_u32_e32 v40, 0x1c00, v92
	v_add_u32_e32 v44, 0x1840, v92
	v_add_u32_e32 v56, 0x1c40, v92
	v_add_u32_e32 v60, 0x1880, v92
	v_add_u32_e32 v72, 0x1c80, v92
	v_add_u32_e32 v76, 0x18c0, v92
	v_add_u32_e32 v88, 0x1cc0, v92
	v_ashrrev_i32_e32 v37, 31, v36
	v_ashrrev_i32_e32 v41, 31, v40
	v_ashrrev_i32_e32 v45, 31, v44
	v_ashrrev_i32_e32 v57, 31, v56
	v_ashrrev_i32_e32 v61, 31, v60
	v_ashrrev_i32_e32 v73, 31, v72
	v_ashrrev_i32_e32 v77, 31, v76
	v_ashrrev_i32_e32 v89, 31, v88
	v_lshl_add_u64 v[36:37], v[36:37], 4, s[12:13]
	v_lshl_add_u64 v[40:41], v[40:41], 4, s[12:13]
	v_lshl_add_u64 v[44:45], v[44:45], 4, s[12:13]
	v_lshl_add_u64 v[56:57], v[56:57], 4, s[12:13]
	v_lshl_add_u64 v[60:61], v[60:61], 4, s[12:13]
	v_lshl_add_u64 v[72:73], v[72:73], 4, s[12:13]
	v_lshl_add_u64 v[76:77], v[76:77], 4, s[12:13]
	v_lshl_add_u64 v[88:89], v[88:89], 4, s[12:13]
	v_cvt_pk_bf16_f32 v81, v90, v91
	v_cvt_pk_bf16_f32 v65, v74, v75
	v_cvt_pk_bf16_f32 v67, v78, v79
	v_cvt_pk_bf16_f32 v49, v58, v59
	v_cvt_pk_bf16_f32 v51, v62, v63
	v_cvt_pk_bf16_f32 v55, v38, v39
	v_cvt_pk_bf16_f32 v33, v42, v43
	v_cvt_pk_bf16_f32 v35, v46, v47
	global_load_dwordx4 v[36:39], v[36:37], off
	v_cvt_pk_bf16_f32 v83, v94, v95
	global_load_dwordx4 v[40:43], v[40:41], off
	s_nop 0
	global_load_dwordx4 v[44:47], v[44:45], off
	s_nop 0
	global_load_dwordx4 v[56:59], v[56:57], off
	s_nop 0
	global_load_dwordx4 v[60:63], v[60:61], off
	s_nop 0
	global_load_dwordx4 v[72:75], v[72:73], off
	s_nop 0
	global_load_dwordx4 v[76:79], v[76:77], off
	s_nop 0
	global_load_dwordx4 v[88:91], v[88:89], off
	v_add_u32_e32 v208, 0x2000, v92
	v_add_u32_e32 v210, 0x2400, v92
	v_add_u32_e32 v214, 0x2040, v92
	v_add_u32_e32 v216, 0x2440, v92
	v_add_u32_e32 v220, 0x2080, v92
	v_add_u32_e32 v222, 0x2480, v92
	v_add_u32_e32 v226, 0x20c0, v92
	v_add_u32_e32 v228, 0x24c0, v92
	v_ashrrev_i32_e32 v209, 31, v208
	v_ashrrev_i32_e32 v211, 31, v210
	v_ashrrev_i32_e32 v215, 31, v214
	v_ashrrev_i32_e32 v217, 31, v216
	v_ashrrev_i32_e32 v221, 31, v220
	v_ashrrev_i32_e32 v223, 31, v222
	v_ashrrev_i32_e32 v227, 31, v226
	v_ashrrev_i32_e32 v229, 31, v228
	v_lshl_add_u64 v[208:209], v[208:209], 4, s[12:13]
	v_lshl_add_u64 v[212:213], v[210:211], 4, s[12:13]
	v_lshl_add_u64 v[214:215], v[214:215], 4, s[12:13]
	v_lshl_add_u64 v[218:219], v[216:217], 4, s[12:13]
	v_lshl_add_u64 v[220:221], v[220:221], 4, s[12:13]
	v_lshl_add_u64 v[224:225], v[222:223], 4, s[12:13]
	v_lshl_add_u64 v[226:227], v[226:227], 4, s[12:13]
	v_lshl_add_u64 v[230:231], v[228:229], 4, s[12:13]
	global_load_dwordx4 v[168:171], v[208:209], off
	global_load_dwordx4 v[172:175], v[212:213], off
	global_load_dwordx4 v[176:179], v[214:215], off
	global_load_dwordx4 v[180:183], v[218:219], off
	global_load_dwordx4 v[184:187], v[220:221], off
	global_load_dwordx4 v[188:191], v[224:225], off
	global_load_dwordx4 v[192:195], v[226:227], off
	global_load_dwordx4 v[196:199], v[230:231], off
	s_waitcnt vmcnt(8)
	v_mfma_f32_32x32x16_bf16 v[16:31], v[36:39], v[96:99], v[16:31]
	v_mfma_f32_32x32x16_bf16 v[16:31], v[40:43], v[84:87], v[16:31]
	v_mfma_f32_32x32x16_bf16 v[16:31], v[44:47], v[80:83], v[16:31]
	v_mfma_f32_32x32x16_bf16 v[16:31], v[56:59], v[64:67], v[16:31]
	v_mfma_f32_32x32x16_bf16 v[16:31], v[60:63], v[68:71], v[16:31]
	v_mfma_f32_32x32x16_bf16 v[16:31], v[72:75], v[52:55], v[16:31]
	v_mfma_f32_32x32x16_bf16 v[16:31], v[76:79], v[48:51], v[16:31]
	v_mfma_f32_32x32x16_bf16 v[16:31], v[88:91], v[32:35], v[16:31]
	s_waitcnt vmcnt(0)
	v_mfma_f32_32x32x16_bf16 v[0:15], v[168:171], v[96:99], v[0:15]
	v_mfma_f32_32x32x16_bf16 v[0:15], v[172:175], v[84:87], v[0:15]
	v_mfma_f32_32x32x16_bf16 v[0:15], v[176:179], v[80:83], v[0:15]
	v_mfma_f32_32x32x16_bf16 v[0:15], v[180:183], v[64:67], v[0:15]
	v_mfma_f32_32x32x16_bf16 v[0:15], v[184:187], v[68:71], v[0:15]
	v_mfma_f32_32x32x16_bf16 v[0:15], v[188:191], v[52:55], v[0:15]
	v_mfma_f32_32x32x16_bf16 v[0:15], v[192:195], v[48:51], v[0:15]
	v_mfma_f32_32x32x16_bf16 v[0:15], v[196:199], v[32:35], v[0:15]
	s_addk_i32 s0, 0x100
	s_cmpk_eq_i32 s0, 0x400
	v_add_u32_e32 v131, 64, v131
	s_cbranch_scc0 .LBB0_308
	v_readlane_b32 s0, v251, 50
	v_bfe_u32 v230, v206, 6, 2
	v_lshlrev_b32_e32 v231, 2, v165
	v_add_u32_e32 v232, s0, v166
	v_readlane_b32 s0, v251, 53
	v_lshl_or_b32 v232, v232, 6, v231
	v_lshlrev_b32_e32 v230, 5, v230
	v_readlane_b32 s2, v251, 56
	v_or3_b32 v230, v230, s0, v164
	v_readlane_b32 s0, v253, 59
	v_lshlrev_b32_e32 v128, 1, v230
	v_readlane_b32 s1, v253, 60
	v_ashrrev_i32_e32 v233, 31, v232
	v_readlane_b32 s3, v251, 57
	v_lshl_add_u64 v[228:229], s[0:1], 0, v[128:129]
	s_movk_i32 s4, 0x3800
	v_lshl_add_u64 v[232:233], s[2:3], 0, v[232:233]
	v_mad_u64_u32 v[226:227], s[0:1], v232, s4, v[228:229]
	v_mad_i32_i24 v227, v233, s4, v227
	global_load_ushort v167, v[226:227], off offset:1024
	s_mov_b64 s[0:1], 0x3800
	v_lshl_add_u64 v[220:221], v[226:227], 0, s[0:1]
	global_load_ushort v168, v[220:221], off offset:1024
	s_mov_b64 s[0:1], 0x7000
	v_lshl_add_u64 v[222:223], v[226:227], 0, s[0:1]
	global_load_ushort v169, v[222:223], off offset:1024
	s_mov_b64 s[0:1], 0xa800
	v_lshl_add_u64 v[224:225], v[226:227], 0, s[0:1]
	global_load_ushort v170, v[224:225], off offset:1024
	s_mov_b64 s[0:1], 0x1c000
	v_lshl_add_u64 v[218:219], v[226:227], 0, s[0:1]
	global_load_ushort v171, v[218:219], off offset:1024
	s_mov_b64 s[0:1], 0x1f800
	v_lshl_add_u64 v[220:221], v[226:227], 0, s[0:1]
	global_load_ushort v172, v[220:221], off offset:1024
	s_mov_b64 s[0:1], 0x23000
	v_lshl_add_u64 v[222:223], v[226:227], 0, s[0:1]
	global_load_ushort v173, v[222:223], off offset:1024
	s_mov_b64 s[0:1], 0x26800
	v_lshl_add_u64 v[224:225], v[226:227], 0, s[0:1]
	global_load_ushort v174, v[224:225], off offset:1024
	s_mov_b64 s[0:1], 0x38000
	v_lshl_add_u64 v[218:219], v[226:227], 0, s[0:1]
	global_load_ushort v175, v[218:219], off offset:1024
	s_mov_b64 s[0:1], 0x3b800
	v_lshl_add_u64 v[220:221], v[226:227], 0, s[0:1]
	global_load_ushort v176, v[220:221], off offset:1024
	s_mov_b64 s[0:1], 0x3f000
	v_lshl_add_u64 v[222:223], v[226:227], 0, s[0:1]
	global_load_ushort v177, v[222:223], off offset:1024
	s_mov_b64 s[0:1], 0x42800
	v_lshl_add_u64 v[224:225], v[226:227], 0, s[0:1]
	global_load_ushort v178, v[224:225], off offset:1024
	s_mov_b64 s[0:1], 0x54000
	v_lshl_add_u64 v[218:219], v[226:227], 0, s[0:1]
	global_load_ushort v179, v[218:219], off offset:1024
	s_mov_b64 s[0:1], 0x57800
	v_lshl_add_u64 v[220:221], v[226:227], 0, s[0:1]
	global_load_ushort v180, v[220:221], off offset:1024
	s_mov_b64 s[0:1], 0x5b000
	v_lshl_add_u64 v[222:223], v[226:227], 0, s[0:1]
	global_load_ushort v181, v[222:223], off offset:1024
	s_mov_b64 s[0:1], 0x5e800
	v_lshl_add_u64 v[224:225], v[226:227], 0, s[0:1]
	global_load_ushort v182, v[224:225], off offset:1024
	s_mov_b64 s[0:1], 0x70000
	v_lshl_add_u64 v[218:219], v[226:227], 0, s[0:1]
	global_load_ushort v183, v[218:219], off offset:1024
	s_mov_b64 s[0:1], 0x73800
	v_lshl_add_u64 v[220:221], v[226:227], 0, s[0:1]
	global_load_ushort v184, v[220:221], off offset:1024
	s_mov_b64 s[0:1], 0x77000
	v_lshl_add_u64 v[222:223], v[226:227], 0, s[0:1]
	global_load_ushort v185, v[222:223], off offset:1024
	s_mov_b64 s[0:1], 0x7a800
	v_lshl_add_u64 v[224:225], v[226:227], 0, s[0:1]
	global_load_ushort v186, v[224:225], off offset:1024
	s_mov_b64 s[0:1], 0x8c000
	v_lshl_add_u64 v[218:219], v[226:227], 0, s[0:1]
	global_load_ushort v187, v[218:219], off offset:1024
	s_mov_b64 s[0:1], 0x8f800
	v_lshl_add_u64 v[220:221], v[226:227], 0, s[0:1]
	global_load_ushort v188, v[220:221], off offset:1024
	s_mov_b64 s[0:1], 0x93000
	v_lshl_add_u64 v[222:223], v[226:227], 0, s[0:1]
	global_load_ushort v189, v[222:223], off offset:1024
	s_mov_b64 s[0:1], 0x96800
	v_lshl_add_u64 v[224:225], v[226:227], 0, s[0:1]
	global_load_ushort v190, v[224:225], off offset:1024
	s_mov_b64 s[0:1], 0xa8000
	v_lshl_add_u64 v[218:219], v[226:227], 0, s[0:1]
	global_load_ushort v191, v[218:219], off offset:1024
	s_mov_b64 s[0:1], 0xab800
	v_lshl_add_u64 v[220:221], v[226:227], 0, s[0:1]
	global_load_ushort v192, v[220:221], off offset:1024
	s_mov_b64 s[0:1], 0xaf000
	v_lshl_add_u64 v[222:223], v[226:227], 0, s[0:1]
	global_load_ushort v193, v[222:223], off offset:1024
	s_mov_b64 s[0:1], 0xb2800
	v_lshl_add_u64 v[224:225], v[226:227], 0, s[0:1]
	global_load_ushort v194, v[224:225], off offset:1024
	s_mov_b64 s[0:1], 0xc4000
	v_lshl_add_u64 v[218:219], v[226:227], 0, s[0:1]
	global_load_ushort v195, v[218:219], off offset:1024
	s_mov_b64 s[0:1], 0xc7800
	v_lshl_add_u64 v[220:221], v[226:227], 0, s[0:1]
	global_load_ushort v196, v[220:221], off offset:1024
	s_mov_b64 s[0:1], 0xcb000
	v_lshl_add_u64 v[222:223], v[226:227], 0, s[0:1]
	global_load_ushort v197, v[222:223], off offset:1024
	s_mov_b64 s[0:1], 0xce800
	v_lshl_add_u64 v[224:225], v[226:227], 0, s[0:1]
	global_load_ushort v198, v[224:225], off offset:1024
	v_readlane_b32 s0, v251, 25
	v_readlane_b32 s1, v251, 26
	v_lshlrev_b32_e32 v128, 1, v230
	v_lshlrev_b64 v[224:225], 10, v[232:233]
	v_lshl_add_u64 v[228:229], s[0:1], 0, v[128:129]
	v_lshl_add_u64 v[228:229], v[228:229], 0, v[224:225]
	s_waitcnt vmcnt(0)
	v_lshlrev_b32_e32 v167, 16, v167
	v_mul_f32_e32 v207, 0xbfb8aa3b, v167
	v_exp_f32_e32 v207, v207
	v_lshlrev_b32_e32 v168, 16, v168
	v_mul_f32_e32 v208, 0xbfb8aa3b, v168
	v_exp_f32_e32 v208, v208
	v_lshlrev_b32_e32 v169, 16, v169
	v_mul_f32_e32 v209, 0xbfb8aa3b, v169
	v_exp_f32_e32 v209, v209
	v_lshlrev_b32_e32 v170, 16, v170
	v_mul_f32_e32 v210, 0xbfb8aa3b, v170
	v_exp_f32_e32 v210, v210
	v_lshlrev_b32_e32 v171, 16, v171
	v_mul_f32_e32 v211, 0xbfb8aa3b, v171
	v_exp_f32_e32 v211, v211
	v_lshlrev_b32_e32 v172, 16, v172
	v_mul_f32_e32 v212, 0xbfb8aa3b, v172
	v_exp_f32_e32 v212, v212
	v_lshlrev_b32_e32 v173, 16, v173
	v_mul_f32_e32 v213, 0xbfb8aa3b, v173
	v_exp_f32_e32 v213, v213
	v_lshlrev_b32_e32 v174, 16, v174
	v_mul_f32_e32 v214, 0xbfb8aa3b, v174
	v_exp_f32_e32 v214, v214
	v_lshlrev_b32_e32 v175, 16, v175
	v_mul_f32_e32 v215, 0xbfb8aa3b, v175
	v_exp_f32_e32 v215, v215
	v_lshlrev_b32_e32 v176, 16, v176
	v_mul_f32_e32 v216, 0xbfb8aa3b, v176
	v_exp_f32_e32 v216, v216
	v_lshlrev_b32_e32 v177, 16, v177
	v_mul_f32_e32 v217, 0xbfb8aa3b, v177
	v_exp_f32_e32 v217, v217
	v_lshlrev_b32_e32 v178, 16, v178
	v_mul_f32_e32 v218, 0xbfb8aa3b, v178
	v_exp_f32_e32 v218, v218
	v_lshlrev_b32_e32 v179, 16, v179
	v_mul_f32_e32 v219, 0xbfb8aa3b, v179
	v_exp_f32_e32 v219, v219
	v_lshlrev_b32_e32 v180, 16, v180
	v_mul_f32_e32 v220, 0xbfb8aa3b, v180
	v_exp_f32_e32 v220, v220
	v_lshlrev_b32_e32 v181, 16, v181
	v_mul_f32_e32 v221, 0xbfb8aa3b, v181
	v_exp_f32_e32 v221, v221
	v_lshlrev_b32_e32 v182, 16, v182
	v_mul_f32_e32 v222, 0xbfb8aa3b, v182
	v_exp_f32_e32 v222, v222
	s_nop 0
	v_add_f32_e32 v207, 1.0, v207
	v_add_f32_e32 v208, 1.0, v208
	v_add_f32_e32 v209, 1.0, v209
	v_add_f32_e32 v210, 1.0, v210
	v_add_f32_e32 v211, 1.0, v211
	v_add_f32_e32 v212, 1.0, v212
	v_add_f32_e32 v213, 1.0, v213
	v_add_f32_e32 v214, 1.0, v214
	v_add_f32_e32 v215, 1.0, v215
	v_add_f32_e32 v216, 1.0, v216
	v_add_f32_e32 v217, 1.0, v217
	v_add_f32_e32 v218, 1.0, v218
	v_add_f32_e32 v219, 1.0, v219
	v_add_f32_e32 v220, 1.0, v220
	v_add_f32_e32 v221, 1.0, v221
	v_add_f32_e32 v222, 1.0, v222
	v_rcp_f32_e32 v207, v207
	v_rcp_f32_e32 v208, v208
	v_rcp_f32_e32 v209, v209
	v_rcp_f32_e32 v210, v210
	v_rcp_f32_e32 v211, v211
	v_rcp_f32_e32 v212, v212
	v_rcp_f32_e32 v213, v213
	v_rcp_f32_e32 v214, v214
	v_rcp_f32_e32 v215, v215
	v_rcp_f32_e32 v216, v216
	v_rcp_f32_e32 v217, v217
	v_rcp_f32_e32 v218, v218
	v_rcp_f32_e32 v219, v219
	v_rcp_f32_e32 v220, v220
	v_rcp_f32_e32 v221, v221
	v_rcp_f32_e32 v222, v222
	s_nop 0
	v_mul_f32_e32 v167, v207, v167
	v_mul_f32_e32 v168, v208, v168
	v_mul_f32_e32 v169, v209, v169
	v_mul_f32_e32 v170, v210, v170
	v_mul_f32_e32 v171, v211, v171
	v_mul_f32_e32 v172, v212, v172
	v_mul_f32_e32 v173, v213, v173
	v_mul_f32_e32 v174, v214, v174
	v_mul_f32_e32 v175, v215, v175
	v_mul_f32_e32 v176, v216, v176
	v_mul_f32_e32 v177, v217, v177
	v_mul_f32_e32 v178, v218, v178
	v_mul_f32_e32 v179, v219, v179
	v_mul_f32_e32 v180, v220, v180
	v_mul_f32_e32 v181, v221, v181
	v_mul_f32_e32 v182, v222, v182
	v_lshlrev_b32_e32 v183, 16, v183
	v_mul_f32_e32 v207, 0xbfb8aa3b, v183
	v_exp_f32_e32 v207, v207
	v_lshlrev_b32_e32 v184, 16, v184
	v_mul_f32_e32 v208, 0xbfb8aa3b, v184
	v_exp_f32_e32 v208, v208
	v_lshlrev_b32_e32 v185, 16, v185
	v_mul_f32_e32 v209, 0xbfb8aa3b, v185
	v_exp_f32_e32 v209, v209
	v_lshlrev_b32_e32 v186, 16, v186
	v_mul_f32_e32 v210, 0xbfb8aa3b, v186
	v_exp_f32_e32 v210, v210
	v_lshlrev_b32_e32 v187, 16, v187
	v_mul_f32_e32 v211, 0xbfb8aa3b, v187
	v_exp_f32_e32 v211, v211
	v_lshlrev_b32_e32 v188, 16, v188
	v_mul_f32_e32 v212, 0xbfb8aa3b, v188
	v_exp_f32_e32 v212, v212
	v_lshlrev_b32_e32 v189, 16, v189
	v_mul_f32_e32 v213, 0xbfb8aa3b, v189
	v_exp_f32_e32 v213, v213
	v_lshlrev_b32_e32 v190, 16, v190
	v_mul_f32_e32 v214, 0xbfb8aa3b, v190
	v_exp_f32_e32 v214, v214
	v_lshlrev_b32_e32 v191, 16, v191
	v_mul_f32_e32 v215, 0xbfb8aa3b, v191
	v_exp_f32_e32 v215, v215
	v_lshlrev_b32_e32 v192, 16, v192
	v_mul_f32_e32 v216, 0xbfb8aa3b, v192
	v_exp_f32_e32 v216, v216
	v_lshlrev_b32_e32 v193, 16, v193
	v_mul_f32_e32 v217, 0xbfb8aa3b, v193
	v_exp_f32_e32 v217, v217
	v_lshlrev_b32_e32 v194, 16, v194
	v_mul_f32_e32 v218, 0xbfb8aa3b, v194
	v_exp_f32_e32 v218, v218
	v_lshlrev_b32_e32 v195, 16, v195
	v_mul_f32_e32 v219, 0xbfb8aa3b, v195
	v_exp_f32_e32 v219, v219
	v_lshlrev_b32_e32 v196, 16, v196
	v_mul_f32_e32 v220, 0xbfb8aa3b, v196
	v_exp_f32_e32 v220, v220
	v_lshlrev_b32_e32 v197, 16, v197
	v_mul_f32_e32 v221, 0xbfb8aa3b, v197
	v_exp_f32_e32 v221, v221
	v_lshlrev_b32_e32 v198, 16, v198
	v_mul_f32_e32 v222, 0xbfb8aa3b, v198
	v_exp_f32_e32 v222, v222
	s_nop 0
	v_add_f32_e32 v207, 1.0, v207
	v_add_f32_e32 v208, 1.0, v208
	v_add_f32_e32 v209, 1.0, v209
	v_add_f32_e32 v210, 1.0, v210
	v_add_f32_e32 v211, 1.0, v211
	v_add_f32_e32 v212, 1.0, v212
	v_add_f32_e32 v213, 1.0, v213
	v_add_f32_e32 v214, 1.0, v214
	v_add_f32_e32 v215, 1.0, v215
	v_add_f32_e32 v216, 1.0, v216
	v_add_f32_e32 v217, 1.0, v217
	v_add_f32_e32 v218, 1.0, v218
	v_add_f32_e32 v219, 1.0, v219
	v_add_f32_e32 v220, 1.0, v220
	v_add_f32_e32 v221, 1.0, v221
	v_add_f32_e32 v222, 1.0, v222
	v_rcp_f32_e32 v207, v207
	v_rcp_f32_e32 v208, v208
	v_rcp_f32_e32 v209, v209
	v_rcp_f32_e32 v210, v210
	v_rcp_f32_e32 v211, v211
	v_rcp_f32_e32 v212, v212
	v_rcp_f32_e32 v213, v213
	v_rcp_f32_e32 v214, v214
	v_rcp_f32_e32 v215, v215
	v_rcp_f32_e32 v216, v216
	v_rcp_f32_e32 v217, v217
	v_rcp_f32_e32 v218, v218
	v_rcp_f32_e32 v219, v219
	v_rcp_f32_e32 v220, v220
	v_rcp_f32_e32 v221, v221
	v_rcp_f32_e32 v222, v222
	s_nop 0
	v_mul_f32_e32 v183, v207, v183
	v_mul_f32_e32 v184, v208, v184
	v_mul_f32_e32 v185, v209, v185
	v_mul_f32_e32 v186, v210, v186
	v_mul_f32_e32 v187, v211, v187
	v_mul_f32_e32 v188, v212, v188
	v_mul_f32_e32 v189, v213, v189
	v_mul_f32_e32 v190, v214, v190
	v_mul_f32_e32 v191, v215, v191
	v_mul_f32_e32 v192, v216, v192
	v_mul_f32_e32 v193, v217, v193
	v_mul_f32_e32 v194, v218, v194
	v_mul_f32_e32 v195, v219, v195
	v_mul_f32_e32 v196, v220, v196
	v_mul_f32_e32 v197, v221, v197
	v_mul_f32_e32 v198, v222, v198
	v_mul_f32_e32 v16, 0x3bb504f3, v16
	v_mul_f32_e32 v17, 0x3bb504f3, v17
	v_mul_f32_e32 v18, 0x3bb504f3, v18
	v_mul_f32_e32 v19, 0x3bb504f3, v19
	v_mul_f32_e32 v20, 0x3bb504f3, v20
	v_mul_f32_e32 v21, 0x3bb504f3, v21
	v_mul_f32_e32 v22, 0x3bb504f3, v22
	v_mul_f32_e32 v23, 0x3bb504f3, v23
	v_mul_f32_e32 v24, 0x3bb504f3, v24
	v_mul_f32_e32 v25, 0x3bb504f3, v25
	v_mul_f32_e32 v26, 0x3bb504f3, v26
	v_mul_f32_e32 v27, 0x3bb504f3, v27
	v_mul_f32_e32 v28, 0x3bb504f3, v28
	v_mul_f32_e32 v29, 0x3bb504f3, v29
	v_mul_f32_e32 v30, 0x3bb504f3, v30
	v_mul_f32_e32 v31, 0x3bb504f3, v31
	v_mul_f32_e32 v0, 0x3bb504f3, v0
	v_mul_f32_e32 v1, 0x3bb504f3, v1
	v_mul_f32_e32 v2, 0x3bb504f3, v2
	v_mul_f32_e32 v3, 0x3bb504f3, v3
	v_mul_f32_e32 v4, 0x3bb504f3, v4
	v_mul_f32_e32 v5, 0x3bb504f3, v5
	v_mul_f32_e32 v6, 0x3bb504f3, v6
	v_mul_f32_e32 v7, 0x3bb504f3, v7
	v_mul_f32_e32 v8, 0x3bb504f3, v8
	v_mul_f32_e32 v9, 0x3bb504f3, v9
	v_mul_f32_e32 v10, 0x3bb504f3, v10
	v_mul_f32_e32 v11, 0x3bb504f3, v11
	v_mul_f32_e32 v12, 0x3bb504f3, v12
	v_mul_f32_e32 v13, 0x3bb504f3, v13
	v_mul_f32_e32 v14, 0x3bb504f3, v14
	v_mul_f32_e32 v15, 0x3bb504f3, v15
	v_mul_f32_e32 v16, v16, v167
	v_mul_f32_e32 v17, v17, v168
	v_mul_f32_e32 v18, v18, v169
	v_mul_f32_e32 v19, v19, v170
	v_mul_f32_e32 v20, v20, v171
	v_mul_f32_e32 v21, v21, v172
	v_mul_f32_e32 v22, v22, v173
	v_mul_f32_e32 v23, v23, v174
	v_mul_f32_e32 v24, v24, v175
	v_mul_f32_e32 v25, v25, v176
	v_mul_f32_e32 v26, v26, v177
	v_mul_f32_e32 v27, v27, v178
	v_mul_f32_e32 v28, v28, v179
	v_mul_f32_e32 v29, v29, v180
	v_mul_f32_e32 v30, v30, v181
	v_mul_f32_e32 v31, v31, v182
	v_mul_f32_e32 v0, v0, v183
	v_mul_f32_e32 v1, v1, v184
	v_mul_f32_e32 v2, v2, v185
	v_mul_f32_e32 v3, v3, v186
	v_mul_f32_e32 v4, v4, v187
	v_mul_f32_e32 v5, v5, v188
	v_mul_f32_e32 v6, v6, v189
	v_mul_f32_e32 v7, v7, v190
	v_mul_f32_e32 v8, v8, v191
	v_mul_f32_e32 v9, v9, v192
	v_mul_f32_e32 v10, v10, v193
	v_mul_f32_e32 v11, v11, v194
	v_mul_f32_e32 v12, v12, v195
	v_mul_f32_e32 v13, v13, v196
	v_mul_f32_e32 v14, v14, v197
	v_mul_f32_e32 v15, v15, v198
	v_cvt_pk_bf16_f32 v207, v16, v17
	v_mov_b64_e32 v[216:217], v[228:229]
	global_store_short v[216:217], v207, off
	global_store_short_d16_hi v[216:217], v207, off offset:1024
	v_cvt_pk_bf16_f32 v208, v18, v19
	s_mov_b64 s[0:1], 0x800
	v_lshl_add_u64 v[218:219], v[228:229], 0, s[0:1]
	global_store_short v[218:219], v208, off
	global_store_short_d16_hi v[218:219], v208, off offset:1024
	v_cvt_pk_bf16_f32 v209, v20, v21
	s_mov_b64 s[0:1], 0x2000
	v_lshl_add_u64 v[220:221], v[228:229], 0, s[0:1]
	global_store_short v[220:221], v209, off
	global_store_short_d16_hi v[220:221], v209, off offset:1024
	v_cvt_pk_bf16_f32 v210, v22, v23
	s_mov_b64 s[0:1], 0x2800
	v_lshl_add_u64 v[222:223], v[228:229], 0, s[0:1]
	global_store_short v[222:223], v210, off
	global_store_short_d16_hi v[222:223], v210, off offset:1024
	v_cvt_pk_bf16_f32 v211, v24, v25
	s_mov_b64 s[0:1], 0x4000
	v_lshl_add_u64 v[216:217], v[228:229], 0, s[0:1]
	global_store_short v[216:217], v211, off
	global_store_short_d16_hi v[216:217], v211, off offset:1024
	v_cvt_pk_bf16_f32 v212, v26, v27
	s_mov_b64 s[0:1], 0x4800
	v_lshl_add_u64 v[218:219], v[228:229], 0, s[0:1]
	global_store_short v[218:219], v212, off
	global_store_short_d16_hi v[218:219], v212, off offset:1024
	v_cvt_pk_bf16_f32 v213, v28, v29
	s_mov_b64 s[0:1], 0x6000
	v_lshl_add_u64 v[220:221], v[228:229], 0, s[0:1]
	global_store_short v[220:221], v213, off
	global_store_short_d16_hi v[220:221], v213, off offset:1024
	v_cvt_pk_bf16_f32 v214, v30, v31
	s_mov_b64 s[0:1], 0x6800
	v_lshl_add_u64 v[222:223], v[228:229], 0, s[0:1]
	global_store_short v[222:223], v214, off
	global_store_short_d16_hi v[222:223], v214, off offset:1024
	v_cvt_pk_bf16_f32 v207, v0, v1
	s_mov_b64 s[0:1], 0x8000
	v_lshl_add_u64 v[216:217], v[228:229], 0, s[0:1]
	global_store_short v[216:217], v207, off
	global_store_short_d16_hi v[216:217], v207, off offset:1024
	v_cvt_pk_bf16_f32 v208, v2, v3
	s_mov_b64 s[0:1], 0x8800
	v_lshl_add_u64 v[218:219], v[228:229], 0, s[0:1]
	global_store_short v[218:219], v208, off
	global_store_short_d16_hi v[218:219], v208, off offset:1024
	v_cvt_pk_bf16_f32 v209, v4, v5
	s_mov_b64 s[0:1], 0xa000
	v_lshl_add_u64 v[220:221], v[228:229], 0, s[0:1]
	global_store_short v[220:221], v209, off
	global_store_short_d16_hi v[220:221], v209, off offset:1024
	v_cvt_pk_bf16_f32 v210, v6, v7
	s_mov_b64 s[0:1], 0xa800
	v_lshl_add_u64 v[222:223], v[228:229], 0, s[0:1]
	global_store_short v[222:223], v210, off
	global_store_short_d16_hi v[222:223], v210, off offset:1024
	v_cvt_pk_bf16_f32 v211, v8, v9
	s_mov_b64 s[0:1], 0xc000
	v_lshl_add_u64 v[216:217], v[228:229], 0, s[0:1]
	global_store_short v[216:217], v211, off
	global_store_short_d16_hi v[216:217], v211, off offset:1024
	v_cvt_pk_bf16_f32 v212, v10, v11
	s_mov_b64 s[0:1], 0xc800
	v_lshl_add_u64 v[218:219], v[228:229], 0, s[0:1]
	global_store_short v[218:219], v212, off
	global_store_short_d16_hi v[218:219], v212, off offset:1024
	v_cvt_pk_bf16_f32 v213, v12, v13
	s_mov_b64 s[0:1], 0xe000
	v_lshl_add_u64 v[220:221], v[228:229], 0, s[0:1]
	global_store_short v[220:221], v213, off
	global_store_short_d16_hi v[220:221], v213, off offset:1024
	v_cvt_pk_bf16_f32 v214, v14, v15
	s_mov_b64 s[0:1], 0xe800
	v_lshl_add_u64 v[222:223], v[228:229], 0, s[0:1]
	global_store_short v[222:223], v214, off
	global_store_short_d16_hi v[222:223], v214, off offset:1024
